# combo9: combo8 barrier + XCD-local barriers (no L2 writeback, poll per-XCD counter) at the P4-P5, P5-P6, P6-P1 seams, whose producer/consumer row blocks stay on one XCD; runtime check of XCC==blockIdx
# baseline (speedup 1.0000x reference)
; #define LAS __attribute__((address_space(3)))
; __device__ __forceinline__ unsigned xb_add(unsigned* p, unsigned v) { return __hip_atomic_fetch_add(p, v, __ATOMIC_RELAXED, __HIP_MEMORY_SCOPE_AGENT); }
; __device__ __forceinline__ unsigned xb_xcc_id() { return (unsigned)__builtin_amdgcn_s_getreg((3 << 11) | 20) & 0xFu; }
; __device__ __forceinline__ XcdBarrier xcd_barrier_post(unsigned* bar, volatile LAS unsigned* st) {
;     XcdBarrier b; b.bar = bar; b.x = xb_xcc_id(); b.st = st;
;     if (threadIdx.x == 0) (void)xb_add(&bar[XB_XCNT(b.x)], 1u);
;     return b;
; __global__ void __launch_bounds__(512, 2) mega_fwd(Args a) {
;     ...
;     volatile LAS unsigned* MISC = (volatile LAS unsigned*)(ldsl + MISC_OFF);
;     if (tid < 16) MISC[tid] = 0u;
;     __syncthreads();
;     const XcdBarrier xbar = xcd_barrier_post((unsigned*)(ws + WS_BAR), MISC);
_Z8mega_fwd4Args:
	s_mov_b32 s66, s2
	s_load_dword s33, s[0:1], 0x138
	s_load_dwordx2 s[10:11], s[0:1], 0x130
	s_load_dwordx8 s[68:75], s[0:1], 0x0
	s_load_dwordx4 s[88:91], s[0:1], 0xa0
	s_load_dwordx2 s[2:3], s[0:1], 0x20
	v_and_b32_e32 v190, 0x3ff, v0
	s_add_u32 s12, s0, 0x130
	v_mov_b32_e32 v1, v190
	s_addc_u32 s13, s1, 0
	s_nop 0
	v_readfirstlane_b32 s24, v1
	v_cmp_gt_i32_e32 vcc, 16, v1
	s_and_saveexec_b64 s[4:5], vcc
	v_lshl_add_u32 v2, v1, 2, 0
	v_add_u32_e32 v2, 0x26800, v2
	v_mov_b32_e32 v3, 0
	ds_write_b32 v2, v3
	s_or_b64 exec, exec, s[4:5]
	s_waitcnt lgkmcnt(0)
	s_add_u32 s4, s90, 0x2e80000
	s_addc_u32 s5, s91, 0
	v_writelane_b32 v252, s4, 0
	s_barrier
	s_nop 0
	v_writelane_b32 v252, s5, 1
	s_getreg_b32 s4, hwreg(HW_REG_XCC_ID, 0, 4)
	s_and_b32 s4, s4, 15
	v_writelane_b32 v252, s4, 2
	s_and_b32 s5, s66, 7
	s_cmp_eq_u32 s5, s4
	s_cbranch_scc1 .Lxcc_ok
	v_readlane_b32 s98, v252, 0
	v_readlane_b32 s99, v252, 1
	s_add_u32 s98, s98, 0x3520
	s_addc_u32 s99, s99, 0
	s_mov_b64 s[6:7], exec
	s_mov_b64 exec, 1
	v_mov_b32_e32 v250, 1
	v_mov_b32_e32 v251, 0
	global_atomic_add v251, v250, s[98:99]
	s_mov_b64 exec, s[6:7]
.Lxcc_ok:
	v_cmp_eq_u32_e64 s[6:7], 0, v190
	s_mov_b64 s[4:5], exec
	s_nop 0
	v_writelane_b32 v252, s6, 3
	s_nop 1
	v_writelane_b32 v252, s7, 4
	s_and_b64 s[6:7], s[4:5], s[6:7]
	s_mov_b64 exec, s[6:7]
	s_cbranch_execz .LBB0_5
	s_mov_b64 s[6:7], exec
	v_mbcnt_lo_u32_b32 v2, s6, 0
	v_mbcnt_hi_u32_b32 v2, s7, v2
	v_cmp_eq_u32_e32 vcc, 0, v2
	s_and_b64 s[8:9], exec, vcc
	s_mov_b64 exec, s[8:9]
	s_cbranch_execz .LBB0_5
	v_readlane_b32 s8, v252, 2
	s_bcnt1_i32_b64 s6, s[6:7]
	s_lshl_b32 s8, s8, 8
	v_mov_b32_e32 v3, s6
	v_readlane_b32 s6, v252, 0
	v_mov_b32_e32 v2, s8
	v_readlane_b32 s7, v252, 1
	s_nop 4
	global_atomic_add v2, v3, s[6:7] offset:1024

; __device__ __forceinline__ unsigned xb_add(unsigned* p, unsigned v) { return __hip_atomic_fetch_add(p, v, __ATOMIC_RELAXED, __HIP_MEMORY_SCOPE_AGENT); }
; __device__ __forceinline__ void xcd_barrier(const XcdBarrier& b) {
;     ...
;     if (threadIdx.x == 0) {
;         unsigned* bar = b.bar; unsigned bx = b.x; asm volatile("" : "+s"(bx));
;         __builtin_amdgcn_s_waitcnt(0);
;         unsigned nloc = b.st[0], nx = b.st[1];
;         if (nloc == 0u) { xcd_barrier_complete(bar, bx, nloc, nx); b.st[0] = nloc; b.st[1] = nx; }
;         const unsigned old = xb_add(&bar[XB_XSUB(bx)], 1u);
;         const unsigned gen = old / nloc;
;         if (old + 1u == (gen + 1u) * nloc) {
.LBB0_243:
	s_waitcnt vmcnt(0)
	s_barrier
	s_mov_b64 s[0:1], exec
	v_readlane_b32 s2, v252, 3
	v_readlane_b32 s3, v252, 4
	s_and_b64 s[2:3], s[0:1], s[2:3]
	s_mov_b64 exec, s[2:3]
	s_cbranch_execz .LBB0_295
	s_waitcnt vmcnt(0) lgkmcnt(0)
	v_mov_b32_e32 v0, 0x26800
	ds_read_b32 v2, v0
	ds_read_b32 v3, v0 offset:4
	ds_read_b32 v8, v0 offset:8
	ds_read_b32 v9, v0 offset:12
	v_readlane_b32 s10, v252, 0
	v_readlane_b32 s11, v252, 1
	v_readlane_b32 s12, v252, 2
	s_lshl_b32 s12, s12, 8
	s_add_u32 s14, s10, s12
	s_addc_u32 s15, s11, 0
	s_add_u32 s14, s14, 0x1400
	s_addc_u32 s15, s15, 0
	s_add_u32 s16, s10, 0x3400
	s_addc_u32 s17, s11, 0
	v_mov_b32_e32 v4, 1
	global_atomic_add v5, v161, v4, s[14:15] sc0
	s_waitcnt lgkmcnt(0)
	v_readfirstlane_b32 s18, v2
	v_readfirstlane_b32 s19, v3
	v_cvt_f32_u32_e32 v7, v2
	v_rcp_f32_e32 v7, v7
	s_waitcnt vmcnt(0)
	v_readfirstlane_b32 s13, v5
	v_cvt_f32_u32_e32 v6, v5
	v_mul_f32_e32 v6, v6, v7
	v_cvt_u32_f32_e32 v6, v6
	s_nop 0
	v_readfirstlane_b32 s2, v6
	s_mul_i32 s3, s2, s18
	s_cmp_gt_u32 s3, s13
	s_cbranch_scc0 .Lxb0_a
	s_sub_i32 s2, s2, 1
	s_sub_i32 s3, s3, s18

; __device__ __forceinline__ unsigned xb_ld(unsigned* p)              { return __hip_atomic_load(p, __ATOMIC_RELAXED, __HIP_MEMORY_SCOPE_AGENT); }
; __device__ __forceinline__ unsigned xb_add(unsigned* p, unsigned v) { return __hip_atomic_fetch_add(p, v, __ATOMIC_RELAXED, __HIP_MEMORY_SCOPE_AGENT); }
; #define XB_SPIN(cond, bar) do { unsigned _sp = 0; while (cond) { __builtin_amdgcn_s_sleep(1); \
;     if ((++_sp & 255u) == 0u) { if (xb_ld(&(bar)[XB_TMO])) break; if (_sp > XB_SPIN_CAP) { atomicAdd(&(bar)[XB_TMO], 1u); break; } } } } while (0)
; __device__ __forceinline__ void xcd_barrier(const XcdBarrier& b) {
;     ...
;             const unsigned tg = og / nx;
;             if (og + 1u == (tg + 1u) * nx) xb_add(&bar[XB_TOPGEN], 1u);
;             else XB_SPIN(xb_ld(&bar[XB_TOPGEN]) == tg, bar);
.Lxb0_poll:
	v_readfirstlane_b32 s2, v8
	s_add_i32 s2, s2, 2
	s_mul_i32 s2, s2, s19
	v_add_u32_e32 v8, 1, v8
	ds_write_b32 v0, v8 offset:8
.Lxb0_pollinit:
	s_mov_b32 s3, 0

; __device__ __forceinline__ unsigned xb_ld(unsigned* p)              { return __hip_atomic_load(p, __ATOMIC_RELAXED, __HIP_MEMORY_SCOPE_AGENT); }
; __device__ __forceinline__ unsigned xb_add(unsigned* p, unsigned v) { return __hip_atomic_fetch_add(p, v, __ATOMIC_RELAXED, __HIP_MEMORY_SCOPE_AGENT); }
; #define XB_SPIN(cond, bar) do { unsigned _sp = 0; while (cond) { __builtin_amdgcn_s_sleep(1); \
;     if ((++_sp & 255u) == 0u) { if (xb_ld(&(bar)[XB_TMO])) break; if (_sp > XB_SPIN_CAP) { atomicAdd(&(bar)[XB_TMO], 1u); break; } } } } while (0)
; __device__ __forceinline__ void xcd_barrier(const XcdBarrier& b) {
;     ...
;             __builtin_amdgcn_fence(__ATOMIC_ACQUIRE, "agent");
;             xb_add(&bar[XB_XGEN(bx)], 1u);
;             asm volatile("s_waitcnt vmcnt(0)" ::: "memory");
;         } else {
;             XB_SPIN(xb_ld(&bar[XB_XGEN(bx)]) == gen, bar);
;             __builtin_amdgcn_fence(__ATOMIC_ACQUIRE, "agent");
;             asm volatile("s_waitcnt vmcnt(0)" ::: "memory");
.Lxb0_go:
	v_readfirstlane_b32 s12, v9
	s_cmp_lg_u32 s12, 0
	s_cbranch_scc1 .Lxb0_moded
	s_add_u32 s10, s10, 0x3520
	s_addc_u32 s11, s11, 0
	global_load_dword v5, v161, s[10:11] sc1
	s_waitcnt vmcnt(0)
	v_readfirstlane_b32 s12, v5
	s_cmp_eq_u32 s12, 0
	s_cselect_b32 s12, 1, 2
	s_cmp_eq_u32 s18, 32
	s_cselect_b32 s12, s12, 2
	s_cmp_eq_u32 s19, 8
	s_cselect_b32 s12, s12, 2
	v_mov_b32_e32 v9, s12
	ds_write_b32 v0, v9 offset:12
.Lxb0_moded:
	buffer_inv sc1
	s_waitcnt vmcnt(0) lgkmcnt(0)

; __device__ __forceinline__ unsigned xb_add(unsigned* p, unsigned v) { return __hip_atomic_fetch_add(p, v, __ATOMIC_RELAXED, __HIP_MEMORY_SCOPE_AGENT); }
; __device__ __forceinline__ void xcd_barrier(const XcdBarrier& b) {
;     ...
;     if (threadIdx.x == 0) {
;         unsigned* bar = b.bar; unsigned bx = b.x; asm volatile("" : "+s"(bx));
;         __builtin_amdgcn_s_waitcnt(0);
;         unsigned nloc = b.st[0], nx = b.st[1];
;         if (nloc == 0u) { xcd_barrier_complete(bar, bx, nloc, nx); b.st[0] = nloc; b.st[1] = nx; }
;         const unsigned old = xb_add(&bar[XB_XSUB(bx)], 1u);
;         const unsigned gen = old / nloc;
;         if (old + 1u == (gen + 1u) * nloc) {
.LBB0_303:
	s_or_b64 exec, exec, s[2:3]
	s_waitcnt vmcnt(0)
	s_waitcnt vmcnt(63) expcnt(7) lgkmcnt(15)
	s_barrier
	s_mov_b64 s[0:1], exec
	v_readlane_b32 s2, v252, 3
	v_readlane_b32 s3, v252, 4
	s_and_b64 s[2:3], s[0:1], s[2:3]
	s_mov_b64 exec, s[2:3]
	s_cbranch_execz .LBB0_355
	s_waitcnt vmcnt(0) lgkmcnt(0)
	v_mov_b32_e32 v0, 0x26800
	ds_read_b32 v2, v0
	ds_read_b32 v3, v0 offset:4
	ds_read_b32 v8, v0 offset:8
	ds_read_b32 v9, v0 offset:12
	v_readlane_b32 s10, v252, 0
	v_readlane_b32 s11, v252, 1
	v_readlane_b32 s12, v252, 2
	s_lshl_b32 s12, s12, 8
	s_add_u32 s14, s10, s12
	s_addc_u32 s15, s11, 0
	s_add_u32 s14, s14, 0x1400
	s_addc_u32 s15, s15, 0
	s_add_u32 s16, s10, 0x3400
	s_addc_u32 s17, s11, 0
	v_mov_b32_e32 v4, 1
	global_atomic_add v5, v161, v4, s[14:15] sc0
	s_waitcnt lgkmcnt(0)
	v_readfirstlane_b32 s18, v2
	v_readfirstlane_b32 s19, v3
	v_cvt_f32_u32_e32 v7, v2
	v_rcp_f32_e32 v7, v7
	s_waitcnt vmcnt(0)
	v_readfirstlane_b32 s13, v5
	v_cvt_f32_u32_e32 v6, v5
	v_mul_f32_e32 v6, v6, v7
	v_cvt_u32_f32_e32 v6, v6
	s_nop 0
	v_readfirstlane_b32 s2, v6
	s_mul_i32 s3, s2, s18
	s_cmp_gt_u32 s3, s13
	s_cbranch_scc0 .Lxb1_a
	s_sub_i32 s2, s2, 1
	s_sub_i32 s3, s3, s18

; __device__ __forceinline__ unsigned xb_add(unsigned* p, unsigned v) { return __hip_atomic_fetch_add(p, v, __ATOMIC_RELAXED, __HIP_MEMORY_SCOPE_AGENT); }
; __device__ __forceinline__ void xcd_barrier(const XcdBarrier& b) {
;     ...
;     if (threadIdx.x == 0) {
;         unsigned* bar = b.bar; unsigned bx = b.x; asm volatile("" : "+s"(bx));
;         __builtin_amdgcn_s_waitcnt(0);
;         unsigned nloc = b.st[0], nx = b.st[1];
;         if (nloc == 0u) { xcd_barrier_complete(bar, bx, nloc, nx); b.st[0] = nloc; b.st[1] = nx; }
;         const unsigned old = xb_add(&bar[XB_XSUB(bx)], 1u);
;         const unsigned gen = old / nloc;
;         if (old + 1u == (gen + 1u) * nloc) {
.LBB0_482:
	s_or_b64 exec, exec, s[0:1]
	s_waitcnt vmcnt(0)
	s_barrier
	s_mov_b64 s[0:1], exec
	v_readlane_b32 s2, v252, 3
	v_readlane_b32 s3, v252, 4
	s_and_b64 s[2:3], s[0:1], s[2:3]
	s_mov_b64 exec, s[2:3]
	s_cbranch_execz .LBB0_534
	s_waitcnt vmcnt(0) lgkmcnt(0)
	v_mov_b32_e32 v0, 0x26800
	ds_read_b32 v2, v0
	ds_read_b32 v3, v0 offset:4
	ds_read_b32 v8, v0 offset:8
	ds_read_b32 v9, v0 offset:12
	v_readlane_b32 s10, v252, 0
	v_readlane_b32 s11, v252, 1
	v_readlane_b32 s12, v252, 2
	s_lshl_b32 s12, s12, 8
	s_add_u32 s14, s10, s12
	s_addc_u32 s15, s11, 0
	s_add_u32 s14, s14, 0x1400
	s_addc_u32 s15, s15, 0
	s_add_u32 s16, s10, 0x3400
	s_addc_u32 s17, s11, 0
	v_mov_b32_e32 v4, 1
	global_atomic_add v5, v161, v4, s[14:15] sc0
	s_waitcnt lgkmcnt(0)
	v_readfirstlane_b32 s18, v2
	v_readfirstlane_b32 s19, v3
	v_cvt_f32_u32_e32 v7, v2
	v_rcp_f32_e32 v7, v7
	s_waitcnt vmcnt(0)
	v_readfirstlane_b32 s13, v5
	v_cvt_f32_u32_e32 v6, v5
	v_mul_f32_e32 v6, v6, v7
	v_cvt_u32_f32_e32 v6, v6
	s_nop 0
	v_readfirstlane_b32 s2, v6
	s_mul_i32 s3, s2, s18
	s_cmp_gt_u32 s3, s13
	s_cbranch_scc0 .Lxb2_a
	s_sub_i32 s2, s2, 1
	s_sub_i32 s3, s3, s18

; __device__ __forceinline__ unsigned xb_add(unsigned* p, unsigned v) { return __hip_atomic_fetch_add(p, v, __ATOMIC_RELAXED, __HIP_MEMORY_SCOPE_AGENT); }
; __device__ __forceinline__ void xcd_barrier(const XcdBarrier& b) {
;     ...
;     if (threadIdx.x == 0) {
;         unsigned* bar = b.bar; unsigned bx = b.x; asm volatile("" : "+s"(bx));
;         __builtin_amdgcn_s_waitcnt(0);
;         unsigned nloc = b.st[0], nx = b.st[1];
;         if (nloc == 0u) { xcd_barrier_complete(bar, bx, nloc, nx); b.st[0] = nloc; b.st[1] = nx; }
;         const unsigned old = xb_add(&bar[XB_XSUB(bx)], 1u);
;         const unsigned gen = old / nloc;
;         if (old + 1u == (gen + 1u) * nloc) {
.LBB0_880:
	s_or_b64 exec, exec, s[0:1]
	s_waitcnt vmcnt(0)
	s_barrier
	s_mov_b64 s[0:1], exec
	v_readlane_b32 s2, v252, 3
	v_readlane_b32 s3, v252, 4
	s_and_b64 s[2:3], s[0:1], s[2:3]
	s_mov_b32 s26, 0xbfb8aa3b
	s_mov_b32 s27, 0x800000
	s_mov_b32 s28, 0x3f317217
	s_mov_b32 s29, 0x7f800000
	v_readlane_b32 s20, v254, 55
	v_readlane_b32 s21, v254, 56
	s_mov_b64 exec, s[2:3]
	s_cbranch_execz .LBB0_932
	s_waitcnt vmcnt(0) lgkmcnt(0)
	v_mov_b32_e32 v0, 0x26800
	ds_read_b32 v2, v0
	ds_read_b32 v3, v0 offset:4
	ds_read_b32 v8, v0 offset:8
	ds_read_b32 v9, v0 offset:12
	v_readlane_b32 s10, v252, 0
	v_readlane_b32 s11, v252, 1
	v_readlane_b32 s12, v252, 2
	s_lshl_b32 s12, s12, 8
	s_add_u32 s14, s10, s12
	s_addc_u32 s15, s11, 0
	s_add_u32 s14, s14, 0x1400
	s_addc_u32 s15, s15, 0
	s_add_u32 s16, s10, 0x3400
	s_addc_u32 s17, s11, 0
	v_mov_b32_e32 v4, 1
	global_atomic_add v5, v161, v4, s[14:15] sc0
	s_waitcnt lgkmcnt(0)
	v_readfirstlane_b32 s18, v2
	v_readfirstlane_b32 s19, v3
	v_cvt_f32_u32_e32 v7, v2
	v_rcp_f32_e32 v7, v7
	s_waitcnt vmcnt(0)
	v_readfirstlane_b32 s13, v5
	v_cvt_f32_u32_e32 v6, v5
	v_mul_f32_e32 v6, v6, v7
	v_cvt_u32_f32_e32 v6, v6
	s_nop 0
	v_readfirstlane_b32 s2, v6
	s_mul_i32 s3, s2, s18
	s_cmp_gt_u32 s3, s13
	s_cbranch_scc0 .Lxb3_a
	s_sub_i32 s2, s2, 1
	s_sub_i32 s3, s3, s18

; __device__ __forceinline__ unsigned xb_add(unsigned* p, unsigned v) { return __hip_atomic_fetch_add(p, v, __ATOMIC_RELAXED, __HIP_MEMORY_SCOPE_AGENT); }
; __device__ __forceinline__ void xcd_barrier(const XcdBarrier& b) {
;     ...
;     if (threadIdx.x == 0) {
;         unsigned* bar = b.bar; unsigned bx = b.x; asm volatile("" : "+s"(bx));
;         __builtin_amdgcn_s_waitcnt(0);
;         unsigned nloc = b.st[0], nx = b.st[1];
;         if (nloc == 0u) { xcd_barrier_complete(bar, bx, nloc, nx); b.st[0] = nloc; b.st[1] = nx; }
;         const unsigned old = xb_add(&bar[XB_XSUB(bx)], 1u);
;         const unsigned gen = old / nloc;
;         if (old + 1u == (gen + 1u) * nloc) {
.LBB0_1070:
	s_waitcnt vmcnt(0)
	s_waitcnt lgkmcnt(0)
	s_barrier
	s_mov_b64 s[0:1], exec
	v_readlane_b32 s2, v252, 3
	v_readlane_b32 s3, v252, 4
	s_and_b64 s[2:3], s[0:1], s[2:3]
	s_mov_b64 s[30:31], 0x2000
	s_mov_b64 exec, s[2:3]
	s_cbranch_execz .LBB0_1122
	s_waitcnt vmcnt(0) lgkmcnt(0)
	v_mov_b32_e32 v0, 0x26800
	ds_read_b32 v2, v0
	ds_read_b32 v3, v0 offset:4
	ds_read_b32 v8, v0 offset:8
	ds_read_b32 v9, v0 offset:12
	v_readlane_b32 s10, v252, 0
	v_readlane_b32 s11, v252, 1
	v_readlane_b32 s12, v252, 2
	s_lshl_b32 s12, s12, 8
	s_add_u32 s14, s10, s12
	s_addc_u32 s15, s11, 0
	s_add_u32 s14, s14, 0x1400
	s_addc_u32 s15, s15, 0
	s_add_u32 s16, s10, 0x3400
	s_addc_u32 s17, s11, 0
	v_mov_b32_e32 v4, 1
	global_atomic_add v5, v161, v4, s[14:15] sc0
	s_waitcnt lgkmcnt(0)
	v_readfirstlane_b32 s18, v2
	v_readfirstlane_b32 s19, v3
	v_cvt_f32_u32_e32 v7, v2
	v_rcp_f32_e32 v7, v7
	s_waitcnt vmcnt(0)
	v_readfirstlane_b32 s13, v5
	v_cvt_f32_u32_e32 v6, v5
	v_mul_f32_e32 v6, v6, v7
	v_cvt_u32_f32_e32 v6, v6
	s_nop 0
	v_readfirstlane_b32 s2, v6
	s_mul_i32 s3, s2, s18
	s_cmp_gt_u32 s3, s13
	s_cbranch_scc0 .Lxb4_a
	s_sub_i32 s2, s2, 1
	s_sub_i32 s3, s3, s18

; __device__ __forceinline__ unsigned xb_ld(unsigned* p)              { return __hip_atomic_load(p, __ATOMIC_RELAXED, __HIP_MEMORY_SCOPE_AGENT); }
; __device__ __forceinline__ unsigned xb_add(unsigned* p, unsigned v) { return __hip_atomic_fetch_add(p, v, __ATOMIC_RELAXED, __HIP_MEMORY_SCOPE_AGENT); }
; #define XB_SPIN(cond, bar) do { unsigned _sp = 0; while (cond) { __builtin_amdgcn_s_sleep(1); \
;     if ((++_sp & 255u) == 0u) { if (xb_ld(&(bar)[XB_TMO])) break; if (_sp > XB_SPIN_CAP) { atomicAdd(&(bar)[XB_TMO], 1u); break; } } } } while (0)
; __device__ __forceinline__ void xcd_barrier(const XcdBarrier& b) {
;     ...
;         const unsigned old = xb_add(&bar[XB_XSUB(bx)], 1u);
;         const unsigned gen = old / nloc;
;         if (old + 1u == (gen + 1u) * nloc) {
;             __builtin_amdgcn_fence(__ATOMIC_RELEASE, "agent");
;             asm volatile("s_waitcnt vmcnt(0)" ::: "memory");
;             const unsigned og = xb_add(&bar[XB_TOP], 1u);
;             const unsigned tg = og / nx;
;             if (og + 1u == (tg + 1u) * nx) xb_add(&bar[XB_TOPGEN], 1u);
;             else XB_SPIN(xb_ld(&bar[XB_TOPGEN]) == tg, bar);
.Lxb4_b:
	s_add_i32 s13, s13, 1
	v_readfirstlane_b32 s12, v9
	s_cmp_eq_u32 s12, 1
	s_cbranch_scc0 .Lxb4_glob
	s_mov_b32 s2, s3
	s_mov_b64 s[16:17], s[14:15]
	s_branch .Lxb4_pollinit
.Lxb4_glob:
	s_cmp_eq_u32 s13, s3
	s_cbranch_scc0 .Lxb4_poll
	buffer_wbl2 sc1
	s_waitcnt vmcnt(0)
	global_atomic_add v161, v4, s[16:17]

; __device__ __forceinline__ unsigned xb_add(unsigned* p, unsigned v) { return __hip_atomic_fetch_add(p, v, __ATOMIC_RELAXED, __HIP_MEMORY_SCOPE_AGENT); }
; __device__ __forceinline__ void xcd_barrier(const XcdBarrier& b) {
;     ...
;     if (threadIdx.x == 0) {
;         unsigned* bar = b.bar; unsigned bx = b.x; asm volatile("" : "+s"(bx));
;         __builtin_amdgcn_s_waitcnt(0);
;         unsigned nloc = b.st[0], nx = b.st[1];
;         if (nloc == 0u) { xcd_barrier_complete(bar, bx, nloc, nx); b.st[0] = nloc; b.st[1] = nx; }
;         const unsigned old = xb_add(&bar[XB_XSUB(bx)], 1u);
;         const unsigned gen = old / nloc;
;         if (old + 1u == (gen + 1u) * nloc) {
.LBB0_1352:
	s_waitcnt vmcnt(0) lgkmcnt(0)
	v_mov_b32_e32 v0, 0x26800
	ds_read_b32 v2, v0
	ds_read_b32 v3, v0 offset:4
	ds_read_b32 v8, v0 offset:8
	ds_read_b32 v9, v0 offset:12
	v_readlane_b32 s10, v252, 0
	v_readlane_b32 s11, v252, 1
	v_readlane_b32 s12, v252, 2
	s_lshl_b32 s12, s12, 8
	s_add_u32 s14, s10, s12
	s_addc_u32 s15, s11, 0
	s_add_u32 s14, s14, 0x1400
	s_addc_u32 s15, s15, 0
	s_add_u32 s16, s10, 0x3400
	s_addc_u32 s17, s11, 0
	v_mov_b32_e32 v4, 1
	global_atomic_add v5, v161, v4, s[14:15] sc0
	s_waitcnt lgkmcnt(0)
	v_readfirstlane_b32 s18, v2
	v_readfirstlane_b32 s19, v3
	v_cvt_f32_u32_e32 v7, v2
	v_rcp_f32_e32 v7, v7
	s_waitcnt vmcnt(0)
	v_readfirstlane_b32 s13, v5
	v_cvt_f32_u32_e32 v6, v5
	v_mul_f32_e32 v6, v6, v7
	v_cvt_u32_f32_e32 v6, v6
	s_nop 0
	v_readfirstlane_b32 s2, v6
	s_mul_i32 s3, s2, s18
	s_cmp_gt_u32 s3, s13
	s_cbranch_scc0 .Lxb6_a
	s_sub_i32 s2, s2, 1
	s_sub_i32 s3, s3, s18

; __device__ __forceinline__ void xcd_barrier(const XcdBarrier& b) {
;     ...
;             __builtin_amdgcn_fence(__ATOMIC_ACQUIRE, "agent");
;             asm volatile("s_waitcnt vmcnt(0)" ::: "memory");
;         }
;     }
;     __syncthreads();
.Lxb6_go:
	buffer_inv sc1
	s_waitcnt vmcnt(0) lgkmcnt(0)
	s_mov_b64 s[4:5], 0
	s_getpc_b64 s[98:99]
